# baseline (speedup 1.0000x reference)
; #define LAS __attribute__((address_space(3)))
; template <int S> __device__ __forceinline__ void fsm_chunk(f32x16& c0, f32x16& c1, float& ps, bf16x8& pa0, bf16x8& pa1, bf16x8& pa2, bf16x8& pa3) {
;   if constexpr (S < 8) { c1[2 * S] = __builtin_amdgcn_exp2f(c1[2 * S]); c1[2 * S + 1] = __builtin_amdgcn_exp2f(c1[2 * S + 1]); ps += c0[2 * S]; ps += c0[2 * S + 1]; if constexpr (S > 0) { ps += c1[2 * S - 2]; ps += c1[2 * S - 1]; } asm volatile("" : "+v"(c1), "+v"(ps)); }
;   else if constexpr (S == 8) { ps += c1[14]; ps += c1[15]; PK4(c0, 0, pa0); asm volatile("" : "+v"(pa0), "+v"(ps)); }
;   else if constexpr (S == 9) { PK4(c0, 8, pa1); asm volatile("" : "+v"(pa1)); }
;   else if constexpr (S == 10) { PK4(c1, 0, pa2); asm volatile("" : "+v"(pa2)); }
;   else { PK4(c1, 8, pa3); asm volatile("" : "+v"(pa3)); }
; }
; __device__ __forceinline__ void qk_fsm(f32x16& n0, f32x16& n1, f32x16& c0, f32x16& c1, float alC, float& l_reg, bf16x8& pa0, bf16x8& pa1, bf16x8& pa2, bf16x8& pa3,
;                                        const LAS char* kl, const int (&kx)[4], const bf16x8* qr, const LAS char* qrl) {
;   float ps = 0.f;
;     ...
;   QSLOT(0) QSLOT(1) QSLOT(2) QSLOT(3) QSLOT(4) QSLOT(5) QSLOT(6) QSLOT(7) QSLOT(8) QSLOT(9) QSLOT(10) QSLOT(11)
;     ...
;   { auto rr = __builtin_amdgcn_permlane32_swap(__float_as_uint(ps), __float_as_uint(ps), false, false); ps = __uint_as_float(rr[0]) + __uint_as_float(rr[1]); }
;   l_reg = l_reg * alC + ps;
; }
.LBB0_1011:
	s_add_u32 s4, s12, s31
	s_addc_u32 s5, s13, s9
	s_add_u32 s4, s4, 0x1dd0c000
	s_addc_u32 s5, s5, 0
	s_add_u32 s6, s12, s90
	s_addc_u32 s7, s13, s91
	s_add_u32 s6, s6, 0x25504000
	s_addc_u32 s7, s7, 0
	s_waitcnt lgkmcnt(0)
	ds_read_b128 v[244:247], v186 offset:57600
	ds_read_b128 v[248:251], v187 offset:12544
	ds_read_b128 v[238:241], v215
	v_exp_f32_e32 v64, v64
	v_exp_f32_e32 v65, v65
	v_mfma_f32_32x32x16_bf16 v[112:127], v[230:233], v[128:131], 0
	v_add_f32_e32 v96, 0, v80
	v_add_f32_e32 v162, v81, v96
	s_add_i32 m0, s98, 0x8000
	v_mfma_f32_32x32x16_bf16 v[96:111], v[234:237], v[128:131], 0
	global_load_lds_dwordx4 v177, s[4:5]
	s_waitcnt lgkmcnt(0)
	ds_read_b128 v[230:233], v188 offset:57344
	ds_read_b128 v[234:237], v189 offset:12288
	v_add_f32_e32 v162, v82, v162
	v_add_f32_e32 v162, v83, v162
	v_add_f32_e32 v162, v64, v162
	v_mfma_f32_32x32x16_bf16 v[112:127], v[244:247], v[238:241], v[112:127]
	v_exp_f32_e32 v66, v66
	v_exp_f32_e32 v67, v67
	v_add_f32_e32 v162, v65, v162
	s_add_i32 m0, s98, 0xa000
	v_mfma_f32_32x32x16_bf16 v[96:111], v[248:251], v[238:241], v[96:111]
	global_load_lds_dwordx4 v178, s[4:5]
	s_waitcnt lgkmcnt(0)
	ds_read_b128 v[244:247], v188 offset:57600
	ds_read_b128 v[248:251], v189 offset:12544
	ds_read_b128 v[238:241], v215 offset:1024
	v_add_f32_e32 v162, v84, v162
	v_add_f32_e32 v162, v85, v162
	v_add_f32_e32 v162, v66, v162
	v_mfma_f32_32x32x16_bf16 v[112:127], v[230:233], v[132:135], v[112:127]
	v_exp_f32_e32 v68, v68
	v_exp_f32_e32 v69, v69
	v_add_f32_e32 v162, v67, v162
	s_add_i32 m0, s98, 0xc000
	v_mfma_f32_32x32x16_bf16 v[96:111], v[234:237], v[132:135], v[96:111]
	global_load_lds_dwordx4 v179, s[4:5]
	s_waitcnt lgkmcnt(0)
	ds_read_b128 v[230:233], v190 offset:57344
	ds_read_b128 v[234:237], v191 offset:12288
	v_add_f32_e32 v162, v86, v162
	v_add_f32_e32 v162, v87, v162
	v_add_f32_e32 v162, v68, v162
	v_mfma_f32_32x32x16_bf16 v[112:127], v[244:247], v[238:241], v[112:127]
	v_exp_f32_e32 v70, v70
	v_exp_f32_e32 v71, v71
	v_add_f32_e32 v162, v69, v162
	s_add_i32 m0, s98, 0x4000
	v_mfma_f32_32x32x16_bf16 v[96:111], v[248:251], v[238:241], v[96:111]
	global_load_lds_dwordx4 v180, s[6:7]
	s_waitcnt lgkmcnt(0)
	ds_read_b128 v[244:247], v190 offset:57600
	ds_read_b128 v[248:251], v191 offset:12544
	ds_read_b128 v[238:241], v215 offset:2048
	v_add_f32_e32 v162, v88, v162
	v_add_f32_e32 v162, v89, v162
	v_add_f32_e32 v162, v70, v162
	v_mfma_f32_32x32x16_bf16 v[112:127], v[230:233], v[136:139], v[112:127]
	v_exp_f32_e32 v72, v72
	v_exp_f32_e32 v73, v73
	v_add_f32_e32 v162, v71, v162
	s_add_i32 m0, s98, 0x6000
	v_mfma_f32_32x32x16_bf16 v[96:111], v[234:237], v[136:139], v[96:111]
	global_load_lds_dwordx4 v181, s[6:7]
	s_waitcnt lgkmcnt(0)
	ds_read_b128 v[230:233], v192 offset:57344
	ds_read_b128 v[234:237], v193 offset:12288
	v_add_f32_e32 v162, v90, v162
	v_add_f32_e32 v162, v91, v162
	v_add_f32_e32 v162, v72, v162
	v_mfma_f32_32x32x16_bf16 v[112:127], v[244:247], v[238:241], v[112:127]
	v_exp_f32_e32 v74, v74
	v_exp_f32_e32 v75, v75
	v_add_f32_e32 v162, v73, v162
	v_mfma_f32_32x32x16_bf16 v[96:111], v[248:251], v[238:241], v[96:111]
	s_waitcnt lgkmcnt(0)
	ds_read_b128 v[244:247], v192 offset:57600
	ds_read_b128 v[248:251], v193 offset:12544
	ds_read_b128 v[238:241], v215 offset:3072
	v_add_f32_e32 v162, v92, v162
	v_add_f32_e32 v162, v93, v162
	v_add_f32_e32 v162, v74, v162
	v_mfma_f32_32x32x16_bf16 v[112:127], v[230:233], v[156:159], v[112:127]
	v_exp_f32_e32 v76, v76
	v_exp_f32_e32 v77, v77
	v_add_f32_e32 v162, v75, v162
	v_mfma_f32_32x32x16_bf16 v[96:111], v[234:237], v[156:159], v[96:111]
	s_waitcnt lgkmcnt(0)
	ds_read_b128 v[230:233], v186 offset:57472
	ds_read_b128 v[234:237], v187 offset:12416
	v_add_f32_e32 v162, v94, v162
	v_add_f32_e32 v162, v95, v162
	v_add_f32_e32 v162, v76, v162
	v_mfma_f32_32x32x16_bf16 v[112:127], v[244:247], v[238:241], v[112:127]
	v_exp_f32_e32 v78, v78
	v_exp_f32_e32 v79, v79
	v_add_f32_e32 v162, v77, v162
	v_mfma_f32_32x32x16_bf16 v[96:111], v[248:251], v[238:241], v[96:111]
	s_waitcnt lgkmcnt(0)
	ds_read_b128 v[244:247], v188 offset:57472
	ds_read_b128 v[248:251], v189 offset:12416
	v_add_f32_e32 v162, v162, v78
	v_cvt_pk_bf16_f32 v80, v80, v81
	v_cvt_pk_bf16_f32 v81, v82, v83
	v_cvt_pk_bf16_f32 v82, v84, v85
	v_mfma_f32_32x32x16_bf16 v[112:127], v[230:233], v[152:155], v[112:127]
	v_cvt_pk_bf16_f32 v83, v86, v87
	v_add_f32_e32 v227, v79, v162
	v_permlane32_swap_b32_e32 v80, v82
	v_permlane32_swap_b32_e32 v81, v83
	v_mfma_f32_32x32x16_bf16 v[96:111], v[234:237], v[152:155], v[96:111]
	s_waitcnt lgkmcnt(0)
	ds_read_b128 v[230:233], v190 offset:57472
	ds_read_b128 v[234:237], v191 offset:12416
	v_cvt_pk_bf16_f32 v84, v88, v89
	v_cvt_pk_bf16_f32 v85, v90, v91
	v_cvt_pk_bf16_f32 v86, v92, v93
	v_mfma_f32_32x32x16_bf16 v[112:127], v[244:247], v[148:151], v[112:127]
	v_cvt_pk_bf16_f32 v87, v94, v95
	v_permlane32_swap_b32_e32 v84, v86
	v_mfma_f32_32x32x16_bf16 v[96:111], v[248:251], v[148:151], v[96:111]
	v_permlane32_swap_b32_e32 v85, v87
	s_waitcnt lgkmcnt(0)
	ds_read_b128 v[244:247], v192 offset:57472
	ds_read_b128 v[248:251], v193 offset:12416
	v_cvt_pk_bf16_f32 v64, v64, v65
	v_cvt_pk_bf16_f32 v65, v66, v67
	v_cvt_pk_bf16_f32 v66, v68, v69
	v_mfma_f32_32x32x16_bf16 v[112:127], v[230:233], v[144:147], v[112:127]
	v_cvt_pk_bf16_f32 v67, v70, v71
	v_permlane32_swap_b32_e32 v64, v66
	v_mfma_f32_32x32x16_bf16 v[96:111], v[234:237], v[144:147], v[96:111]
	v_permlane32_swap_b32_e32 v65, v67
	s_waitcnt lgkmcnt(0)
; #define LAS __attribute__((address_space(3)))
; __device__ __forceinline__ float fma_s(float a, float b, float c) { float d; asm volatile("v_fma_f32 %0, %1, %2, %3" : "=v"(d) : "v"(a), "v"(b), "v"(c)); return d; }
; template <int S> __device__ __forceinline__ void psm_chunk(f32x16& p0, f32x16& p1, float& mx, float& m_reg, float& alpha, float& mnC) {
;   constexpr float C = SCALE * 1.4426950408889634f; const float Cv = C;
;   if constexpr (S == 0) { mx = p0[0];
; #pragma unroll
;     for (int r = 1; r < 16; ++r) mx = fmaxf(mx, p0[r]); }
;   else if constexpr (S == 1) {
; #pragma unroll
;     for (int r = 0; r < 16; ++r) mx = fmaxf(mx, p1[r]);
;     { auto rr = __builtin_amdgcn_permlane32_swap(__float_as_uint(mx), __float_as_uint(mx), false, false); mx = fmaxf(__uint_as_float(rr[0]), __uint_as_float(rr[1])); }
;     const float mn = (mx - m_reg > THR / SCALE) ? fmaxf(m_reg, mx) : m_reg; alpha = __builtin_amdgcn_exp2f((m_reg - mn) * C); m_reg = mn; mnC = -mn * C; }
;   else if constexpr (S == 2) {
; #pragma unroll
;     for (int r = 0; r < 8; ++r) p0[r] = fma_s(p0[r], Cv, mnC); }
;   else if constexpr (S == 3) {
; #pragma unroll
;     for (int r = 8; r < 16; ++r) p0[r] = fma_s(p0[r], Cv, mnC);
; #pragma unroll
;     for (int r = 0; r < 4; ++r) p0[r] = __builtin_amdgcn_exp2f(p0[r]); }
;   else if constexpr (S == 4) {
; #pragma unroll
;     for (int r = 0; r < 8; ++r) p1[r] = fma_s(p1[r], Cv, mnC);
; #pragma unroll
;     for (int r = 4; r < 8; ++r) p0[r] = __builtin_amdgcn_exp2f(p0[r]); }
;   else if constexpr (S == 5) {
; #pragma unroll
;     for (int r = 8; r < 16; ++r) p1[r] = fma_s(p1[r], Cv, mnC);
; #pragma unroll
;     for (int r = 8; r < 12; ++r) p0[r] = __builtin_amdgcn_exp2f(p0[r]); }
;   else if constexpr (S == 6) {
; #pragma unroll
;     for (int r = 12; r < 16; ++r) p0[r] = __builtin_amdgcn_exp2f(p0[r]); }
;   if constexpr (S == 0 || S == 1) asm volatile("" : "+v"(mx), "+v"(alpha), "+v"(mnC), "+v"(m_reg));
;   else if constexpr (S < 7) asm volatile("" : "+v"(p0), "+v"(p1));
; }
; __device__ __forceinline__ void pv_psm(f32x16* o, const LAS char* vl, bf16x8 pa0, bf16x8 pa1, bf16x8 pa2, bf16x8 pa3, f32x16& n0, f32x16& n1, float& m_reg, float& alN) {
;   float mx = 0.f, mnC = 0.f;
;     ...
;   VSLOT(0) VSLOT(1) VSLOT(2) VSLOT(3) VSLOT(4) VSLOT(5) VSLOT(6) VSLOT(7)
	ds_read_b64_tr_b16 v[234:235], v184
	ds_read_b64_tr_b16 v[236:237], v184 offset:2048
	ds_read_b64_tr_b16 v[238:239], v184 offset:4096
	ds_read_b64_tr_b16 v[240:241], v184 offset:6144
	v_cvt_pk_bf16_f32 v68, v72, v73
	v_cvt_pk_bf16_f32 v69, v74, v75
	v_cvt_pk_bf16_f32 v70, v76, v77
	v_mfma_f32_32x32x16_bf16 v[112:127], v[244:247], v[140:143], v[112:127]
	v_cvt_pk_bf16_f32 v71, v78, v79
	v_permlane32_swap_b32_e32 v68, v70
	v_mfma_f32_32x32x16_bf16 v[96:111], v[248:251], v[140:143], v[96:111]
	v_permlane32_swap_b32_e32 v69, v71
	v_mov_b32_e32 v229, v227
	s_nop 1
	v_permlane32_swap_b32_e32 v227, v229
	s_waitcnt lgkmcnt(0)
	ds_read_b64_tr_b16 v[72:73], v184 offset:8192
	ds_read_b64_tr_b16 v[74:75], v184 offset:10240
	ds_read_b64_tr_b16 v[76:77], v184 offset:12288
	ds_read_b64_tr_b16 v[78:79], v184 offset:14336
	v_max_f32_e32 v88, v113, v113
	v_max_f32_e32 v89, v112, v112
	v_mfma_f32_32x32x16_bf16 v[0:15], v[80:83], v[234:237], v[0:15]
	v_max_f32_e32 v88, v89, v88
	v_max3_f32 v88, v88, v114, v115
	v_max3_f32 v88, v88, v116, v117
	v_max3_f32 v252, v88, v118, v119
	v_max3_f32 v252, v252, v120, v121
	v_max3_f32 v252, v252, v122, v123
	v_max3_f32 v252, v252, v124, v125
	v_mfma_f32_32x32x16_bf16 v[0:15], v[84:87], v[238:241], v[0:15]
	v_max3_f32 v88, v252, v126, v127
	s_waitcnt lgkmcnt(0)
	ds_read_b64_tr_b16 v[234:235], v184 offset:512
	ds_read_b64_tr_b16 v[236:237], v184 offset:2560
	ds_read_b64_tr_b16 v[238:239], v184 offset:4608
	ds_read_b64_tr_b16 v[240:241], v184 offset:6656
	v_max3_f32 v88, v88, v96, v97
	v_max3_f32 v88, v88, v98, v99
	v_max3_f32 v88, v88, v100, v101
	v_max3_f32 v88, v88, v102, v103
	v_mfma_f32_32x32x16_bf16 v[0:15], v[64:67], v[72:75], v[0:15]
	v_max3_f32 v88, v88, v104, v105
	v_max3_f32 v88, v88, v106, v107
	v_max3_f32 v88, v88, v108, v109
	v_max3_f32 v88, v88, v110, v111
	v_mov_b32_e32 v89, v88
	s_nop 1
	v_permlane32_swap_b32_e32 v88, v89
	v_max_f32_e32 v89, v89, v89
	v_max_f32_e32 v88, v88, v88
	v_max_f32_e32 v88, v88, v89
	v_mfma_f32_32x32x16_bf16 v[0:15], v[68:71], v[76:79], v[0:15]
	v_sub_f32_e32 v89, v88, v228
	v_cmp_lt_f32_e32 vcc, s29, v89
	v_max_f32_e32 v89, v228, v228
	v_max_f32_e32 v89, v89, v88
	v_cndmask_b32_e32 v230, v228, v89, vcc
	v_sub_f32_e32 v89, v228, v230
	v_mul_f32_e32 v89, 0x3dd53b94, v89
	v_exp_f32_e32 v223, v89
	v_mul_f32_e32 v89, 0xbdd53b94, v230
	s_waitcnt lgkmcnt(0)
	ds_read_b64_tr_b16 v[72:73], v184 offset:8704
	ds_read_b64_tr_b16 v[74:75], v184 offset:10752
	ds_read_b64_tr_b16 v[76:77], v184 offset:12800
	ds_read_b64_tr_b16 v[78:79], v184 offset:14848
	v_fma_f32 v112, v112, v211, v89
	v_fma_f32 v113, v113, v211, v89
	v_mfma_f32_32x32x16_bf16 v[48:63], v[80:83], v[234:237], v[48:63]
	v_fma_f32 v114, v114, v211, v89
	v_fma_f32 v115, v115, v211, v89
	v_fma_f32 v116, v116, v211, v89
	v_fma_f32 v117, v117, v211, v89
	v_fma_f32 v118, v118, v211, v89
	v_fma_f32 v119, v119, v211, v89
	v_mfma_f32_32x32x16_bf16 v[48:63], v[84:87], v[238:241], v[48:63]
	s_waitcnt lgkmcnt(0)
	ds_read_b64_tr_b16 v[234:235], v184 offset:1024
	ds_read_b64_tr_b16 v[236:237], v184 offset:3072
	ds_read_b64_tr_b16 v[238:239], v184 offset:5120
	ds_read_b64_tr_b16 v[240:241], v184 offset:7168
	v_fma_f32 v120, v120, v211, v89
	v_fma_f32 v121, v121, v211, v89
	v_mfma_f32_32x32x16_bf16 v[48:63], v[64:67], v[72:75], v[48:63]
	v_fma_f32 v122, v122, v211, v89
	v_fma_f32 v123, v123, v211, v89
	v_fma_f32 v124, v124, v211, v89
	v_exp_f32_e32 v112, v112
	v_exp_f32_e32 v113, v113
	v_exp_f32_e32 v114, v114
	v_exp_f32_e32 v115, v115
	v_mfma_f32_32x32x16_bf16 v[48:63], v[68:71], v[76:79], v[48:63]
	v_fma_f32 v125, v125, v211, v89
	v_fma_f32 v126, v126, v211, v89
	v_fma_f32 v127, v127, v211, v89
	s_nop 0
	s_waitcnt lgkmcnt(0)
	ds_read_b64_tr_b16 v[72:73], v184 offset:9216
	ds_read_b64_tr_b16 v[74:75], v184 offset:11264
	ds_read_b64_tr_b16 v[76:77], v184 offset:13312
	ds_read_b64_tr_b16 v[78:79], v184 offset:15360
	v_fma_f32 v96, v96, v211, v89
	v_fma_f32 v97, v97, v211, v89
	v_mfma_f32_32x32x16_bf16 v[32:47], v[80:83], v[234:237], v[32:47]
	v_fma_f32 v98, v98, v211, v89
	v_fma_f32 v99, v99, v211, v89
	v_fma_f32 v100, v100, v211, v89
	v_exp_f32_e32 v116, v116
	v_exp_f32_e32 v117, v117
	v_exp_f32_e32 v118, v118
	v_exp_f32_e32 v119, v119
	v_mfma_f32_32x32x16_bf16 v[32:47], v[84:87], v[238:241], v[32:47]
	v_fma_f32 v101, v101, v211, v89
	v_fma_f32 v102, v102, v211, v89
	v_fma_f32 v103, v103, v211, v89
	s_nop 0
	s_waitcnt lgkmcnt(0)
	ds_read_b64_tr_b16 v[234:235], v184 offset:1536
	ds_read_b64_tr_b16 v[236:237], v184 offset:3584
	ds_read_b64_tr_b16 v[238:239], v184 offset:5632
	ds_read_b64_tr_b16 v[240:241], v184 offset:7680
	v_fma_f32 v104, v104, v211, v89
	v_fma_f32 v105, v105, v211, v89
	v_mfma_f32_32x32x16_bf16 v[32:47], v[64:67], v[72:75], v[32:47]
	v_fma_f32 v106, v106, v211, v89
	v_fma_f32 v107, v107, v211, v89
	v_fma_f32 v108, v108, v211, v89
	v_exp_f32_e32 v120, v120
	v_exp_f32_e32 v121, v121
	v_exp_f32_e32 v122, v122
	v_exp_f32_e32 v123, v123
	v_mfma_f32_32x32x16_bf16 v[32:47], v[68:71], v[76:79], v[32:47]
	v_fma_f32 v109, v109, v211, v89
	v_fma_f32 v110, v110, v211, v89
	v_fma_f32 v111, v111, v211, v89
	s_nop 0
	s_waitcnt lgkmcnt(0)
	ds_read_b64_tr_b16 v[72:73], v184 offset:9728
	ds_read_b64_tr_b16 v[74:75], v184 offset:11776
	ds_read_b64_tr_b16 v[76:77], v184 offset:13824
	ds_read_b64_tr_b16 v[78:79], v184 offset:15872
	v_exp_f32_e32 v124, v124
	v_exp_f32_e32 v125, v125
	v_exp_f32_e32 v126, v126
	v_exp_f32_e32 v127, v127
	s_waitcnt lgkmcnt(0)
	v_cmp_gt_f32_e32 vcc, 1.0, v223
	s_waitcnt vmcnt(0) lgkmcnt(0)
	s_barrier
; #define LAS __attribute__((address_space(3)))
; __device__ __forceinline__ void qk_fsm(f32x16& n0, f32x16& n1, f32x16& c0, f32x16& c1, float alC, float& l_reg, bf16x8& pa0, bf16x8& pa1, bf16x8& pa2, bf16x8& pa3,
;                                        const LAS char* kl, const int (&kx)[4], const bf16x8* qr, const LAS char* qrl) {
;   float ps = 0.f;
;     ...
;   QSLOT(0) QSLOT(1) QSLOT(2) QSLOT(3) QSLOT(4) QSLOT(5) QSLOT(6) QSLOT(7) QSLOT(8) QSLOT(9) QSLOT(10) QSLOT(11)
;     ...
;   { auto rr = __builtin_amdgcn_permlane32_swap(__float_as_uint(ps), __float_as_uint(ps), false, false); ps = __uint_as_float(rr[0]) + __uint_as_float(rr[1]); }
;   l_reg = l_reg * alC + ps;
; }
	ds_read_b128 v[244:247], v186 offset:32768
	ds_read_b128 v[248:251], v186 offset:45056
	v_mfma_f32_32x32x16_bf16 v[16:31], v[80:83], v[234:237], v[16:31]
	v_mfma_f32_32x32x16_bf16 v[16:31], v[84:87], v[238:241], v[16:31]
	v_mfma_f32_32x32x16_bf16 v[16:31], v[64:67], v[72:75], v[16:31]
	v_mfma_f32_32x32x16_bf16 v[16:31], v[68:71], v[76:79], v[16:31]
	s_cbranch_vccz .LBB0_1015
	s_and_saveexec_b64 s[6:7], s[40:41]
	ds_write_b32 v185, v223 offset:128
	s_or_b64 exec, exec, s[6:7]
	s_waitcnt lgkmcnt(0)
	ds_read_b128 v[64:67], v196 offset:224
	ds_read_b128 v[68:71], v196 offset:192
	ds_read_b128 v[72:75], v196 offset:160
	ds_read_b128 v[76:79], v196 offset:128
	s_waitcnt lgkmcnt(0)
	v_pk_mul_f32 v[12:13], v[12:13], v[64:65]
	v_pk_mul_f32 v[8:9], v[8:9], v[68:69]
	v_pk_mul_f32 v[4:5], v[4:5], v[72:73]
	v_pk_mul_f32 v[14:15], v[14:15], v[66:67]
	v_pk_mul_f32 v[10:11], v[10:11], v[70:71]
	v_pk_mul_f32 v[6:7], v[6:7], v[74:75]
	v_pk_mul_f32 v[2:3], v[2:3], v[78:79]
	v_pk_mul_f32 v[0:1], v[0:1], v[76:77]
	v_pk_mul_f32 v[60:61], v[60:61], v[64:65]
	v_pk_mul_f32 v[56:57], v[56:57], v[68:69]
	v_pk_mul_f32 v[52:53], v[52:53], v[72:73]
	v_pk_mul_f32 v[62:63], v[62:63], v[66:67]
	v_pk_mul_f32 v[58:59], v[58:59], v[70:71]
	v_pk_mul_f32 v[54:55], v[54:55], v[74:75]
	v_pk_mul_f32 v[50:51], v[50:51], v[78:79]
	v_pk_mul_f32 v[48:49], v[48:49], v[76:77]
	v_pk_mul_f32 v[44:45], v[44:45], v[64:65]
	v_pk_mul_f32 v[40:41], v[40:41], v[68:69]
	v_pk_mul_f32 v[36:37], v[36:37], v[72:73]
	v_pk_mul_f32 v[46:47], v[46:47], v[66:67]
	v_pk_mul_f32 v[42:43], v[42:43], v[70:71]
	v_pk_mul_f32 v[38:39], v[38:39], v[74:75]
	v_pk_mul_f32 v[34:35], v[34:35], v[78:79]
	v_pk_mul_f32 v[32:33], v[32:33], v[76:77]
	v_pk_mul_f32 v[28:29], v[28:29], v[64:65]
	v_pk_mul_f32 v[24:25], v[24:25], v[68:69]
	v_pk_mul_f32 v[20:21], v[20:21], v[72:73]
	v_pk_mul_f32 v[30:31], v[30:31], v[66:67]
	v_pk_mul_f32 v[26:27], v[26:27], v[70:71]
	v_pk_mul_f32 v[22:23], v[22:23], v[74:75]
	v_pk_mul_f32 v[18:19], v[18:19], v[78:79]
	v_pk_mul_f32 v[16:17], v[16:17], v[76:77]
.LBB0_1015:
	s_add_u32 s4, s12, s31
	s_addc_u32 s5, s13, s9
	s_add_u32 s4, s4, 0x1dd12000
	s_addc_u32 s5, s5, 0
	s_add_u32 s6, s12, s90
	s_addc_u32 s7, s13, s91
	s_add_u32 s6, s6, 0x25508000
	s_addc_u32 s7, s7, 0
	s_waitcnt lgkmcnt(0)
	ds_read_b128 v[232:235], v186 offset:33024
	ds_read_b128 v[236:239], v186 offset:45312
	ds_read_b128 v[240:243], v215
	v_exp_f32_e32 v96, v96
	v_exp_f32_e32 v97, v97
	v_mfma_f32_32x32x16_bf16 v[80:95], v[244:247], v[128:131], 0
	v_add_f32_e32 v64, 0, v112
	v_add_f32_e32 v162, v113, v64
	s_add_i32 m0, s98, 0xe000
	v_mfma_f32_32x32x16_bf16 v[64:79], v[248:251], v[128:131], 0
	global_load_lds_dwordx4 v177, s[4:5]
	s_waitcnt lgkmcnt(0)
	ds_read_b128 v[244:247], v188 offset:32768
	ds_read_b128 v[248:251], v188 offset:45056
	v_add_f32_e32 v162, v114, v162
	v_add_f32_e32 v162, v115, v162
	v_add_f32_e32 v162, v96, v162
	v_mfma_f32_32x32x16_bf16 v[80:95], v[232:235], v[240:243], v[80:95]
	v_exp_f32_e32 v98, v98
	v_exp_f32_e32 v99, v99
	v_add_f32_e32 v162, v97, v162
	s_add_i32 m0, s98, 0x10000
	v_mfma_f32_32x32x16_bf16 v[64:79], v[236:239], v[240:243], v[64:79]
	global_load_lds_dwordx4 v178, s[4:5]
	s_waitcnt lgkmcnt(0)
	ds_read_b128 v[232:235], v188 offset:33024
	ds_read_b128 v[236:239], v188 offset:45312
	ds_read_b128 v[240:243], v215 offset:1024
	v_add_f32_e32 v162, v116, v162
	v_add_f32_e32 v162, v117, v162
	v_add_f32_e32 v162, v98, v162
	v_mfma_f32_32x32x16_bf16 v[80:95], v[244:247], v[132:135], v[80:95]
	v_exp_f32_e32 v100, v100
	v_exp_f32_e32 v101, v101
	v_add_f32_e32 v162, v99, v162
	s_add_i32 m0, s98, 0x12000
	v_mfma_f32_32x32x16_bf16 v[64:79], v[248:251], v[132:135], v[64:79]
	global_load_lds_dwordx4 v179, s[4:5]
	s_waitcnt lgkmcnt(0)
	ds_read_b128 v[244:247], v190 offset:32768
	ds_read_b128 v[248:251], v190 offset:45056
	v_add_f32_e32 v162, v118, v162
	v_add_f32_e32 v162, v119, v162
	v_add_f32_e32 v162, v100, v162
	v_mfma_f32_32x32x16_bf16 v[80:95], v[232:235], v[240:243], v[80:95]
	v_exp_f32_e32 v102, v102
	v_exp_f32_e32 v103, v103
	v_add_f32_e32 v162, v101, v162
	s_mov_b32 m0, s98
	v_mfma_f32_32x32x16_bf16 v[64:79], v[236:239], v[240:243], v[64:79]
	global_load_lds_dwordx4 v180, s[6:7]
	s_waitcnt lgkmcnt(0)
	ds_read_b128 v[232:235], v190 offset:33024
	ds_read_b128 v[236:239], v190 offset:45312
	ds_read_b128 v[240:243], v215 offset:2048
	v_add_f32_e32 v162, v120, v162
	v_add_f32_e32 v162, v121, v162
	v_add_f32_e32 v162, v102, v162
	v_mfma_f32_32x32x16_bf16 v[80:95], v[244:247], v[136:139], v[80:95]
	v_exp_f32_e32 v104, v104
	v_exp_f32_e32 v105, v105
	v_add_f32_e32 v162, v103, v162
	s_add_i32 m0, s98, 0x2000
	v_mfma_f32_32x32x16_bf16 v[64:79], v[248:251], v[136:139], v[64:79]
	global_load_lds_dwordx4 v181, s[6:7]
	s_waitcnt lgkmcnt(0)
	ds_read_b128 v[244:247], v192 offset:32768
	ds_read_b128 v[248:251], v192 offset:45056
	v_add_f32_e32 v162, v122, v162
	v_add_f32_e32 v162, v123, v162
	v_add_f32_e32 v162, v104, v162
	v_mfma_f32_32x32x16_bf16 v[80:95], v[232:235], v[240:243], v[80:95]
	v_exp_f32_e32 v106, v106
	v_exp_f32_e32 v107, v107
	v_add_f32_e32 v162, v105, v162
	v_mfma_f32_32x32x16_bf16 v[64:79], v[236:239], v[240:243], v[64:79]
	s_waitcnt lgkmcnt(0)
	ds_read_b128 v[232:235], v192 offset:33024
	ds_read_b128 v[236:239], v192 offset:45312
	ds_read_b128 v[240:243], v215 offset:3072
	v_add_f32_e32 v162, v124, v162
	v_add_f32_e32 v162, v125, v162
	v_add_f32_e32 v162, v106, v162
	v_mfma_f32_32x32x16_bf16 v[80:95], v[244:247], v[156:159], v[80:95]
	v_exp_f32_e32 v108, v108
	v_exp_f32_e32 v109, v109
	v_add_f32_e32 v162, v107, v162
	v_mfma_f32_32x32x16_bf16 v[64:79], v[248:251], v[156:159], v[64:79]
	s_waitcnt lgkmcnt(0)
; #define LAS __attribute__((address_space(3)))
; __device__ __forceinline__ void qk_fsm(f32x16& n0, f32x16& n1, f32x16& c0, f32x16& c1, float alC, float& l_reg, bf16x8& pa0, bf16x8& pa1, bf16x8& pa2, bf16x8& pa3,
;                                        const LAS char* kl, const int (&kx)[4], const bf16x8* qr, const LAS char* qrl) {
;   float ps = 0.f;
;     ...
;   QSLOT(0) QSLOT(1) QSLOT(2) QSLOT(3) QSLOT(4) QSLOT(5) QSLOT(6) QSLOT(7) QSLOT(8) QSLOT(9) QSLOT(10) QSLOT(11)
;     ...
;   { auto rr = __builtin_amdgcn_permlane32_swap(__float_as_uint(ps), __float_as_uint(ps), false, false); ps = __uint_as_float(rr[0]) + __uint_as_float(rr[1]); }
;   l_reg = l_reg * alC + ps;
; }
; template <int S> __device__ __forceinline__ void psm_chunk(f32x16& p0, f32x16& p1, float& mx, float& m_reg, float& alpha, float& mnC) {
;   constexpr float C = SCALE * 1.4426950408889634f; const float Cv = C;
;   if constexpr (S == 0) { mx = p0[0];
; #pragma unroll
;     for (int r = 1; r < 16; ++r) mx = fmaxf(mx, p0[r]); }
;   else if constexpr (S == 1) {
; #pragma unroll
;     for (int r = 0; r < 16; ++r) mx = fmaxf(mx, p1[r]);
;     { auto rr = __builtin_amdgcn_permlane32_swap(__float_as_uint(mx), __float_as_uint(mx), false, false); mx = fmaxf(__uint_as_float(rr[0]), __uint_as_float(rr[1])); }
;     const float mn = (mx - m_reg > THR / SCALE) ? fmaxf(m_reg, mx) : m_reg; alpha = __builtin_amdgcn_exp2f((m_reg - mn) * C); m_reg = mn; mnC = -mn * C; }
;   else if constexpr (S == 2) {
; #pragma unroll
;     for (int r = 0; r < 8; ++r) p0[r] = fma_s(p0[r], Cv, mnC); }
;   else if constexpr (S == 3) {
; #pragma unroll
;     for (int r = 8; r < 16; ++r) p0[r] = fma_s(p0[r], Cv, mnC);
; #pragma unroll
;     for (int r = 0; r < 4; ++r) p0[r] = __builtin_amdgcn_exp2f(p0[r]); }
;   else if constexpr (S == 4) {
; #pragma unroll
;     for (int r = 0; r < 8; ++r) p1[r] = fma_s(p1[r], Cv, mnC);
; #pragma unroll
;     for (int r = 4; r < 8; ++r) p0[r] = __builtin_amdgcn_exp2f(p0[r]); }
;   else if constexpr (S == 5) {
; #pragma unroll
;     for (int r = 8; r < 16; ++r) p1[r] = fma_s(p1[r], Cv, mnC);
; #pragma unroll
;     for (int r = 8; r < 12; ++r) p0[r] = __builtin_amdgcn_exp2f(p0[r]); }
;   else if constexpr (S == 6) {
; #pragma unroll
;     for (int r = 12; r < 16; ++r) p0[r] = __builtin_amdgcn_exp2f(p0[r]); }
;   if constexpr (S == 0 || S == 1) asm volatile("" : "+v"(mx), "+v"(alpha), "+v"(mnC), "+v"(m_reg));
	ds_read_b128 v[244:247], v186 offset:32896
	ds_read_b128 v[248:251], v186 offset:45184
	v_add_f32_e32 v162, v126, v162
	v_add_f32_e32 v162, v127, v162
	v_add_f32_e32 v162, v108, v162
	v_mfma_f32_32x32x16_bf16 v[80:95], v[232:235], v[240:243], v[80:95]
	v_exp_f32_e32 v110, v110
	v_exp_f32_e32 v111, v111
	v_add_f32_e32 v162, v109, v162
	v_mfma_f32_32x32x16_bf16 v[64:79], v[236:239], v[240:243], v[64:79]
	s_waitcnt lgkmcnt(0)
	ds_read_b128 v[232:235], v188 offset:32896
	ds_read_b128 v[236:239], v188 offset:45184
	v_add_f32_e32 v162, v162, v110
	v_cvt_pk_bf16_f32 v112, v112, v113
	v_cvt_pk_bf16_f32 v113, v114, v115
	v_cvt_pk_bf16_f32 v114, v116, v117
	v_mfma_f32_32x32x16_bf16 v[80:95], v[244:247], v[152:155], v[80:95]
	v_cvt_pk_bf16_f32 v115, v118, v119
	v_add_f32_e32 v231, v111, v162
	v_permlane32_swap_b32_e32 v112, v114
	v_permlane32_swap_b32_e32 v113, v115
	v_mfma_f32_32x32x16_bf16 v[64:79], v[248:251], v[152:155], v[64:79]
	s_waitcnt lgkmcnt(0)
	ds_read_b128 v[244:247], v190 offset:32896
	ds_read_b128 v[248:251], v190 offset:45184
	v_cvt_pk_bf16_f32 v116, v120, v121
	v_cvt_pk_bf16_f32 v117, v122, v123
	v_cvt_pk_bf16_f32 v118, v124, v125
	v_mfma_f32_32x32x16_bf16 v[80:95], v[232:235], v[148:151], v[80:95]
	v_cvt_pk_bf16_f32 v119, v126, v127
	v_permlane32_swap_b32_e32 v116, v118
	v_mfma_f32_32x32x16_bf16 v[64:79], v[236:239], v[148:151], v[64:79]
	v_permlane32_swap_b32_e32 v117, v119
	s_waitcnt lgkmcnt(0)
	ds_read_b128 v[232:235], v192 offset:32896
	ds_read_b128 v[236:239], v192 offset:45184
	v_cvt_pk_bf16_f32 v96, v96, v97
	v_cvt_pk_bf16_f32 v97, v98, v99
	v_cvt_pk_bf16_f32 v98, v100, v101
	v_mfma_f32_32x32x16_bf16 v[80:95], v[244:247], v[144:147], v[80:95]
	v_cvt_pk_bf16_f32 v99, v102, v103
	v_permlane32_swap_b32_e32 v96, v98
	v_mfma_f32_32x32x16_bf16 v[64:79], v[248:251], v[144:147], v[64:79]
	v_permlane32_swap_b32_e32 v97, v99
	s_waitcnt lgkmcnt(0)
	ds_read_b64_tr_b16 v[244:245], v184 offset:16384
	ds_read_b64_tr_b16 v[246:247], v184 offset:18432
	ds_read_b64_tr_b16 v[248:249], v184 offset:20480
	ds_read_b64_tr_b16 v[250:251], v184 offset:22528
	v_cvt_pk_bf16_f32 v100, v104, v105
	v_cvt_pk_bf16_f32 v101, v106, v107
	v_cvt_pk_bf16_f32 v102, v108, v109
	v_mfma_f32_32x32x16_bf16 v[80:95], v[232:235], v[140:143], v[80:95]
	v_cvt_pk_bf16_f32 v103, v110, v111
	v_permlane32_swap_b32_e32 v100, v102
	v_mfma_f32_32x32x16_bf16 v[64:79], v[236:239], v[140:143], v[64:79]
	v_permlane32_swap_b32_e32 v101, v103
	v_mov_b32_e32 v104, v231
	s_nop 1
	v_permlane32_swap_b32_e32 v231, v104
	s_waitcnt lgkmcnt(0)
	ds_read_b64_tr_b16 v[106:107], v184 offset:24576
	ds_read_b64_tr_b16 v[108:109], v184 offset:26624
	ds_read_b64_tr_b16 v[120:121], v184 offset:28672
	ds_read_b64_tr_b16 v[122:123], v184 offset:30720
	v_max_f32_e32 v105, v81, v81
	v_max_f32_e32 v110, v80, v80
	v_mfma_f32_32x32x16_bf16 v[0:15], v[112:115], v[244:247], v[0:15]
	v_max_f32_e32 v105, v110, v105
	v_max3_f32 v105, v105, v82, v83
	v_max3_f32 v105, v105, v84, v85
	v_max3_f32 v105, v105, v86, v87
	v_max3_f32 v105, v105, v88, v89
	v_max3_f32 v105, v105, v90, v91
	v_max3_f32 v105, v105, v92, v93
	v_mfma_f32_32x32x16_bf16 v[0:15], v[116:119], v[248:251], v[0:15]
	v_max3_f32 v105, v105, v94, v95
	s_waitcnt lgkmcnt(0)
	ds_read_b64_tr_b16 v[244:245], v184 offset:16896
	ds_read_b64_tr_b16 v[246:247], v184 offset:18944
	ds_read_b64_tr_b16 v[248:249], v184 offset:20992
	ds_read_b64_tr_b16 v[250:251], v184 offset:23040
	v_max3_f32 v105, v105, v64, v65
	v_max3_f32 v105, v105, v66, v67
	v_max3_f32 v105, v105, v68, v69
	v_max3_f32 v105, v105, v70, v71
	v_mfma_f32_32x32x16_bf16 v[0:15], v[96:99], v[106:109], v[0:15]
	v_max3_f32 v105, v105, v72, v73
	v_max3_f32 v105, v105, v74, v75
	v_max3_f32 v105, v105, v76, v77
	v_max3_f32 v105, v105, v78, v79
	v_mov_b32_e32 v110, v105
	s_nop 1
	v_permlane32_swap_b32_e32 v105, v110
	v_max_f32_e32 v110, v110, v110
	v_max_f32_e32 v105, v105, v105
	v_max_f32_e32 v105, v105, v110
	v_mfma_f32_32x32x16_bf16 v[0:15], v[100:103], v[120:123], v[0:15]
	v_sub_f32_e32 v110, v105, v230
	v_cmp_lt_f32_e32 vcc, s29, v110
	v_max_f32_e32 v110, v230, v230
	v_max_f32_e32 v110, v110, v105
	v_cndmask_b32_e32 v228, v230, v110, vcc
	v_sub_f32_e32 v110, v230, v228
	v_mul_f32_e32 v110, 0x3dd53b94, v110
	v_exp_f32_e32 v162, v110
	v_mul_f32_e32 v110, 0xbdd53b94, v228
	s_waitcnt lgkmcnt(0)
	ds_read_b64_tr_b16 v[106:107], v184 offset:25088
	ds_read_b64_tr_b16 v[108:109], v184 offset:27136
	ds_read_b64_tr_b16 v[120:121], v184 offset:29184
	ds_read_b64_tr_b16 v[122:123], v184 offset:31232
	v_fma_f32 v80, v80, v211, v110
	v_fma_f32 v81, v81, v211, v110
	v_mfma_f32_32x32x16_bf16 v[48:63], v[112:115], v[244:247], v[48:63]
	v_fma_f32 v82, v82, v211, v110
	v_fma_f32 v83, v83, v211, v110
	v_fma_f32 v84, v84, v211, v110
	v_fma_f32 v85, v85, v211, v110
	v_fma_f32 v86, v86, v211, v110
	v_fma_f32 v87, v87, v211, v110
	v_mfma_f32_32x32x16_bf16 v[48:63], v[116:119], v[248:251], v[48:63]
	s_waitcnt lgkmcnt(0)
; #define LAS __attribute__((address_space(3)))
; template <int S> __device__ __forceinline__ void psm_chunk(f32x16& p0, f32x16& p1, float& mx, float& m_reg, float& alpha, float& mnC) {
;   constexpr float C = SCALE * 1.4426950408889634f; const float Cv = C;
;   if constexpr (S == 0) { mx = p0[0];
; #pragma unroll
;     for (int r = 1; r < 16; ++r) mx = fmaxf(mx, p0[r]); }
;   else if constexpr (S == 1) {
; #pragma unroll
;     for (int r = 0; r < 16; ++r) mx = fmaxf(mx, p1[r]);
;     { auto rr = __builtin_amdgcn_permlane32_swap(__float_as_uint(mx), __float_as_uint(mx), false, false); mx = fmaxf(__uint_as_float(rr[0]), __uint_as_float(rr[1])); }
;     const float mn = (mx - m_reg > THR / SCALE) ? fmaxf(m_reg, mx) : m_reg; alpha = __builtin_amdgcn_exp2f((m_reg - mn) * C); m_reg = mn; mnC = -mn * C; }
;   else if constexpr (S == 2) {
; #pragma unroll
;     for (int r = 0; r < 8; ++r) p0[r] = fma_s(p0[r], Cv, mnC); }
;   else if constexpr (S == 3) {
; #pragma unroll
;     for (int r = 8; r < 16; ++r) p0[r] = fma_s(p0[r], Cv, mnC);
; #pragma unroll
;     for (int r = 0; r < 4; ++r) p0[r] = __builtin_amdgcn_exp2f(p0[r]); }
;   else if constexpr (S == 4) {
; #pragma unroll
;     for (int r = 0; r < 8; ++r) p1[r] = fma_s(p1[r], Cv, mnC);
; #pragma unroll
;     for (int r = 4; r < 8; ++r) p0[r] = __builtin_amdgcn_exp2f(p0[r]); }
;   else if constexpr (S == 5) {
; #pragma unroll
;     for (int r = 8; r < 16; ++r) p1[r] = fma_s(p1[r], Cv, mnC);
; #pragma unroll
;     for (int r = 8; r < 12; ++r) p0[r] = __builtin_amdgcn_exp2f(p0[r]); }
;   else if constexpr (S == 6) {
; #pragma unroll
;     for (int r = 12; r < 16; ++r) p0[r] = __builtin_amdgcn_exp2f(p0[r]); }
;   if constexpr (S == 0 || S == 1) asm volatile("" : "+v"(mx), "+v"(alpha), "+v"(mnC), "+v"(m_reg));
;   else if constexpr (S < 7) asm volatile("" : "+v"(p0), "+v"(p1));
; }
; __device__ __forceinline__ void pv_psm(f32x16* o, const LAS char* vl, bf16x8 pa0, bf16x8 pa1, bf16x8 pa2, bf16x8 pa3, f32x16& n0, f32x16& n1, float& m_reg, float& alN) {
;   float mx = 0.f, mnC = 0.f;
;     ...
;   VSLOT(0) VSLOT(1) VSLOT(2) VSLOT(3) VSLOT(4) VSLOT(5) VSLOT(6) VSLOT(7)
; __device__ __forceinline__ void attn_unit(const bf16_t* __restrict__ Qb, const bf16_t* __restrict__ Kh, const bf16_t* __restrict__ Vh, bf16_t* __restrict__ Ob, float* __restrict__ ssq, char* lds, LAS unsigned char* ldsl, ...
;     ...
;   constexpr int NT = SEQ / KVBLK;
	ds_read_b64_tr_b16 v[244:245], v184 offset:17408
	ds_read_b64_tr_b16 v[246:247], v184 offset:19456
	ds_read_b64_tr_b16 v[248:249], v184 offset:21504
	ds_read_b64_tr_b16 v[250:251], v184 offset:23552
	v_fma_f32 v88, v88, v211, v110
	v_fma_f32 v89, v89, v211, v110
	v_mfma_f32_32x32x16_bf16 v[48:63], v[96:99], v[106:109], v[48:63]
	v_fma_f32 v90, v90, v211, v110
	v_fma_f32 v91, v91, v211, v110
	v_fma_f32 v92, v92, v211, v110
	v_exp_f32_e32 v80, v80
	v_exp_f32_e32 v81, v81
	v_exp_f32_e32 v82, v82
	v_exp_f32_e32 v83, v83
	v_mfma_f32_32x32x16_bf16 v[48:63], v[100:103], v[120:123], v[48:63]
	v_fma_f32 v93, v93, v211, v110
	v_fma_f32 v94, v94, v211, v110
	v_fma_f32 v95, v95, v211, v110
	s_nop 0
	s_waitcnt lgkmcnt(0)
	ds_read_b64_tr_b16 v[106:107], v184 offset:25600
	ds_read_b64_tr_b16 v[108:109], v184 offset:27648
	ds_read_b64_tr_b16 v[120:121], v184 offset:29696
	ds_read_b64_tr_b16 v[122:123], v184 offset:31744
	v_fma_f32 v64, v64, v211, v110
	v_fma_f32 v65, v65, v211, v110
	v_mfma_f32_32x32x16_bf16 v[32:47], v[112:115], v[244:247], v[32:47]
	v_fma_f32 v66, v66, v211, v110
	v_fma_f32 v67, v67, v211, v110
	v_fma_f32 v68, v68, v211, v110
	v_exp_f32_e32 v84, v84
	v_exp_f32_e32 v85, v85
	v_exp_f32_e32 v86, v86
	v_exp_f32_e32 v87, v87
	v_mfma_f32_32x32x16_bf16 v[32:47], v[116:119], v[248:251], v[32:47]
	v_fma_f32 v69, v69, v211, v110
	v_fma_f32 v70, v70, v211, v110
	v_fma_f32 v71, v71, v211, v110
	s_nop 0
	s_waitcnt lgkmcnt(0)
	ds_read_b64_tr_b16 v[244:245], v184 offset:17920
	ds_read_b64_tr_b16 v[246:247], v184 offset:19968
	ds_read_b64_tr_b16 v[248:249], v184 offset:22016
	ds_read_b64_tr_b16 v[250:251], v184 offset:24064
	v_fma_f32 v72, v72, v211, v110
	v_fma_f32 v73, v73, v211, v110
	v_mfma_f32_32x32x16_bf16 v[32:47], v[96:99], v[106:109], v[32:47]
	v_fma_f32 v74, v74, v211, v110
	v_fma_f32 v75, v75, v211, v110
	v_fma_f32 v76, v76, v211, v110
	v_exp_f32_e32 v88, v88
	v_exp_f32_e32 v89, v89
	v_exp_f32_e32 v90, v90
	v_exp_f32_e32 v91, v91
	v_mfma_f32_32x32x16_bf16 v[32:47], v[100:103], v[120:123], v[32:47]
	v_fma_f32 v77, v77, v211, v110
	v_fma_f32 v78, v78, v211, v110
	v_fma_f32 v79, v79, v211, v110
	s_nop 0
	s_waitcnt lgkmcnt(0)
	ds_read_b64_tr_b16 v[106:107], v184 offset:26112
	ds_read_b64_tr_b16 v[108:109], v184 offset:28160
	ds_read_b64_tr_b16 v[120:121], v184 offset:30208
	ds_read_b64_tr_b16 v[122:123], v184 offset:32256
	v_exp_f32_e32 v92, v92
	v_exp_f32_e32 v93, v93
	v_exp_f32_e32 v94, v94
	v_exp_f32_e32 v95, v95
	s_waitcnt lgkmcnt(0)
	s_add_i32 s24, s24, 2
	s_add_u32 s31, s31, 0xc000
	s_addc_u32 s9, s9, 0
	v_add_f32_e32 v252, v227, v229
	s_add_u32 s90, s90, 0x8000
	v_fmac_f32_e32 v252, v224, v171
	v_add_f32_e32 v171, v231, v104
	s_addc_u32 s91, s91, 0
	v_fmac_f32_e32 v171, v252, v223
	v_cmp_gt_f32_e32 vcc, 1.0, v162
	s_waitcnt vmcnt(0) lgkmcnt(0)
	s_barrier
	ds_read_b128 v[230:233], v186 offset:57344
	ds_read_b128 v[234:237], v187 offset:12288
	v_mfma_f32_32x32x16_bf16 v[16:31], v[112:115], v[244:247], v[16:31]
	v_mfma_f32_32x32x16_bf16 v[16:31], v[116:119], v[248:251], v[16:31]
	v_mfma_f32_32x32x16_bf16 v[16:31], v[96:99], v[106:109], v[16:31]
	v_mfma_f32_32x32x16_bf16 v[16:31], v[100:103], v[120:123], v[16:31]
	s_cbranch_vccz .LBB0_1019
	s_and_saveexec_b64 s[6:7], s[40:41]
	ds_write_b32 v185, v162 offset:128
	s_or_b64 exec, exec, s[6:7]
	s_waitcnt lgkmcnt(0)
	ds_read_b128 v[96:99], v196 offset:224
	ds_read_b128 v[100:103], v196 offset:192
	ds_read_b128 v[106:109], v196 offset:160
	ds_read_b128 v[110:113], v196 offset:128
	s_waitcnt lgkmcnt(0)
	v_pk_mul_f32 v[12:13], v[12:13], v[96:97]
	v_pk_mul_f32 v[8:9], v[8:9], v[100:101]
	v_pk_mul_f32 v[4:5], v[4:5], v[106:107]
	v_pk_mul_f32 v[14:15], v[14:15], v[98:99]
	v_pk_mul_f32 v[10:11], v[10:11], v[102:103]
	v_pk_mul_f32 v[6:7], v[6:7], v[108:109]
	v_pk_mul_f32 v[2:3], v[2:3], v[112:113]
	v_pk_mul_f32 v[0:1], v[0:1], v[110:111]
	v_pk_mul_f32 v[60:61], v[60:61], v[96:97]
	v_pk_mul_f32 v[56:57], v[56:57], v[100:101]
	v_pk_mul_f32 v[52:53], v[52:53], v[106:107]
	v_pk_mul_f32 v[62:63], v[62:63], v[98:99]
	v_pk_mul_f32 v[58:59], v[58:59], v[102:103]
	v_pk_mul_f32 v[54:55], v[54:55], v[108:109]
	v_pk_mul_f32 v[50:51], v[50:51], v[112:113]
	v_pk_mul_f32 v[48:49], v[48:49], v[110:111]
	v_pk_mul_f32 v[44:45], v[44:45], v[96:97]
	v_pk_mul_f32 v[40:41], v[40:41], v[100:101]
	v_pk_mul_f32 v[36:37], v[36:37], v[106:107]
	v_pk_mul_f32 v[46:47], v[46:47], v[98:99]
	v_pk_mul_f32 v[42:43], v[42:43], v[102:103]
	v_pk_mul_f32 v[38:39], v[38:39], v[108:109]
	v_pk_mul_f32 v[34:35], v[34:35], v[112:113]
	v_pk_mul_f32 v[32:33], v[32:33], v[110:111]
	v_pk_mul_f32 v[28:29], v[28:29], v[96:97]
	v_pk_mul_f32 v[24:25], v[24:25], v[100:101]
	v_pk_mul_f32 v[20:21], v[20:21], v[106:107]
	v_pk_mul_f32 v[30:31], v[30:31], v[98:99]
	v_pk_mul_f32 v[26:27], v[26:27], v[102:103]
	v_pk_mul_f32 v[22:23], v[22:23], v[108:109]
	v_pk_mul_f32 v[18:19], v[18:19], v[112:113]
	v_pk_mul_f32 v[16:17], v[16:17], v[110:111]
